# P9 fp8 K-loop: the s_nop 1 pad in front of each of the 64 scaled MFMAs deleted (no VALU producer of an MFMA operand within 2 states in the loop)
# speedup vs baseline: 1.0110x; 1.0003x over previous
.LBB0_1019:
	ds_read_b128 v[16:19], v183
	ds_read_b128 v[20:23], v183 offset:1024
	ds_read_b128 v[24:27], v183 offset:2048
	ds_read_b128 v[28:31], v183 offset:3072
	ds_read_b128 v[0:3], v184
	ds_read_b128 v[4:7], v184 offset:1024
	ds_read_b128 v[8:11], v184 offset:2048
	ds_read_b128 v[12:15], v184 offset:3072
	s_add_u32 s38, s36, 0xffe00080
	s_addc_u32 s39, s37, -1
	s_cmpk_eq_i32 s60, 0x7c
	s_cselect_b32 s41, s25, s39
	s_cselect_b32 s40, s56, s38
	s_cselect_b32 s39, s23, s59
	s_cselect_b32 s38, s57, s58
	v_lshl_add_u64 v[212:213], s[36:37], 0, v[164:165]
	s_add_i32 m0, s31, 0xc000
	ds_read_b128 v[172:175], v185
	ds_read_b128 v[176:179], v185 offset:1024
	ds_read_b128 v[188:191], v185 offset:2048
	ds_read_b128 v[192:195], v185 offset:3072
	ds_read_b128 v[196:199], v185 offset:4096
	ds_read_b128 v[200:203], v185 offset:5120
	ds_read_b128 v[204:207], v185 offset:6144
	ds_read_b128 v[208:211], v185 offset:7168
	global_load_lds_dwordx4 v[212:213], off
	v_lshl_add_u64 v[212:213], s[36:37], 0, v[166:167]
	s_add_i32 m0, s31, 0xe000
	s_nop 0
	global_load_lds_dwordx4 v[212:213], off
	s_waitcnt vmcnt(8)
	s_waitcnt lgkmcnt(0)
	s_barrier
	s_setprio 1
	s_waitcnt lgkmcnt(0)
	v_mfma_scale_f32_16x16x128_f8f6f4 v[156:159], v[16:23], v[172:179], v[156:159], v186, v186 op_sel_hi:[0,0,0]
	v_mfma_scale_f32_16x16x128_f8f6f4 v[152:155], v[24:31], v[172:179], v[152:155], v186, v186 op_sel_hi:[0,0,0]
	v_mfma_scale_f32_16x16x128_f8f6f4 v[148:151], v[16:23], v[188:195], v[148:151], v186, v186 op_sel_hi:[0,0,0]
	v_mfma_scale_f32_16x16x128_f8f6f4 v[144:147], v[24:31], v[188:195], v[144:147], v186, v186 op_sel_hi:[0,0,0]
	v_mfma_scale_f32_16x16x128_f8f6f4 v[140:143], v[16:23], v[196:203], v[140:143], v186, v186 op_sel_hi:[0,0,0]
	v_mfma_scale_f32_16x16x128_f8f6f4 v[124:127], v[24:31], v[196:203], v[124:127], v186, v186 op_sel_hi:[0,0,0]
	v_mfma_scale_f32_16x16x128_f8f6f4 v[116:119], v[16:23], v[204:211], v[116:119], v186, v186 op_sel_hi:[0,0,0]
	v_mfma_scale_f32_16x16x128_f8f6f4 v[108:111], v[24:31], v[204:211], v[108:111], v186, v186 op_sel_hi:[0,0,0]
	s_setprio 0
	s_setprio 1
	v_mfma_scale_f32_16x16x128_f8f6f4 v[136:139], v[0:7], v[172:179], v[136:139], v186, v186 op_sel_hi:[0,0,0]
	v_mfma_scale_f32_16x16x128_f8f6f4 v[132:135], v[8:15], v[172:179], v[132:135], v186, v186 op_sel_hi:[0,0,0]
	v_mfma_scale_f32_16x16x128_f8f6f4 v[128:131], v[0:7], v[188:195], v[128:131], v186, v186 op_sel_hi:[0,0,0]
	v_mfma_scale_f32_16x16x128_f8f6f4 v[120:123], v[8:15], v[188:195], v[120:123], v186, v186 op_sel_hi:[0,0,0]
	v_mfma_scale_f32_16x16x128_f8f6f4 v[112:115], v[0:7], v[196:203], v[112:115], v186, v186 op_sel_hi:[0,0,0]
	v_mfma_scale_f32_16x16x128_f8f6f4 v[104:107], v[8:15], v[196:203], v[104:107], v186, v186 op_sel_hi:[0,0,0]
	v_mfma_scale_f32_16x16x128_f8f6f4 v[100:103], v[0:7], v[204:211], v[100:103], v186, v186 op_sel_hi:[0,0,0]
	v_mfma_scale_f32_16x16x128_f8f6f4 v[96:99], v[8:15], v[204:211], v[96:99], v186, v186 op_sel_hi:[0,0,0]
	s_setprio 0
	s_barrier
	s_add_i32 s61, s53, s42
	v_lshl_add_u64 v[172:173], s[38:39], 0, v[162:163]
	s_mov_b32 m0, s61
	ds_read_b128 v[188:191], v185 offset:16384
	ds_read_b128 v[192:195], v185 offset:17408
	ds_read_b128 v[196:199], v185 offset:18432
	ds_read_b128 v[200:203], v185 offset:19456
	ds_read_b128 v[204:207], v185 offset:20480
	ds_read_b128 v[208:211], v185 offset:21504
	ds_read_b128 v[212:215], v185 offset:22528
	ds_read_b128 v[216:219], v185 offset:23552
	global_load_lds_dwordx4 v[172:173], off
	s_add_i32 m0, s61, 0x2000
	s_add_u32 s62, s38, 0x200000
	v_lshl_add_u64 v[174:175], s[38:39], 0, v[160:161]
	s_addc_u32 s63, s39, 0
	s_add_i32 s61, s54, s42
	global_load_lds_dwordx4 v[174:175], off
	v_lshl_add_u64 v[176:177], s[62:63], 0, v[162:163]
	s_mov_b32 m0, s61
	v_lshl_add_u64 v[178:179], s[40:41], 0, v[160:161]
	global_load_lds_dwordx4 v[176:177], off
	v_lshl_add_u64 v[176:177], s[62:63], 0, v[160:161]
	s_add_i32 m0, s61, 0x2000
	s_nop 0
	global_load_lds_dwordx4 v[176:177], off
	v_lshl_add_u64 v[176:177], s[40:41], 0, v[162:163]
	s_mov_b32 m0, s31
	s_nop 0
	global_load_lds_dwordx4 v[176:177], off
	s_mov_b32 m0, s44
	s_nop 0
	global_load_lds_dwordx4 v[178:179], off
	s_waitcnt vmcnt(8)
	s_waitcnt lgkmcnt(0)
	s_barrier
	s_setprio 1
	s_waitcnt lgkmcnt(0)
	v_mfma_scale_f32_16x16x128_f8f6f4 v[92:95], v[16:23], v[188:195], v[92:95], v186, v186 op_sel_hi:[0,0,0]
	v_mfma_scale_f32_16x16x128_f8f6f4 v[88:91], v[24:31], v[188:195], v[88:91], v186, v186 op_sel_hi:[0,0,0]
	v_mfma_scale_f32_16x16x128_f8f6f4 v[84:87], v[16:23], v[196:203], v[84:87], v186, v186 op_sel_hi:[0,0,0]
	v_mfma_scale_f32_16x16x128_f8f6f4 v[80:83], v[24:31], v[196:203], v[80:83], v186, v186 op_sel_hi:[0,0,0]
	v_mfma_scale_f32_16x16x128_f8f6f4 v[76:79], v[16:23], v[204:211], v[76:79], v186, v186 op_sel_hi:[0,0,0]
	v_mfma_scale_f32_16x16x128_f8f6f4 v[64:67], v[24:31], v[204:211], v[64:67], v186, v186 op_sel_hi:[0,0,0]
	v_mfma_scale_f32_16x16x128_f8f6f4 v[52:55], v[16:23], v[212:219], v[52:55], v186, v186 op_sel_hi:[0,0,0]
	v_mfma_scale_f32_16x16x128_f8f6f4 v[44:47], v[24:31], v[212:219], v[44:47], v186, v186 op_sel_hi:[0,0,0]
	s_setprio 0
	s_setprio 1
	v_mfma_scale_f32_16x16x128_f8f6f4 v[72:75], v[0:7], v[188:195], v[72:75], v186, v186 op_sel_hi:[0,0,0]
	v_mfma_scale_f32_16x16x128_f8f6f4 v[68:71], v[8:15], v[188:195], v[68:71], v186, v186 op_sel_hi:[0,0,0]
	v_mfma_scale_f32_16x16x128_f8f6f4 v[60:63], v[0:7], v[196:203], v[60:63], v186, v186 op_sel_hi:[0,0,0]
	v_mfma_scale_f32_16x16x128_f8f6f4 v[56:59], v[8:15], v[196:203], v[56:59], v186, v186 op_sel_hi:[0,0,0]
	v_mfma_scale_f32_16x16x128_f8f6f4 v[48:51], v[0:7], v[204:211], v[48:51], v186, v186 op_sel_hi:[0,0,0]
	v_mfma_scale_f32_16x16x128_f8f6f4 v[40:43], v[8:15], v[204:211], v[40:43], v186, v186 op_sel_hi:[0,0,0]
	v_mfma_scale_f32_16x16x128_f8f6f4 v[36:39], v[0:7], v[212:219], v[36:39], v186, v186 op_sel_hi:[0,0,0]
	v_mfma_scale_f32_16x16x128_f8f6f4 v[32:35], v[8:15], v[212:219], v[32:35], v186, v186 op_sel_hi:[0,0,0]
	s_setprio 0
	s_barrier
	s_add_i32 s61, 0, 0x18000
	s_add_i32 s62, 0, 0x1c000
	v_add_u32_e32 v12, s61, v181
	v_add_u32_e32 v28, s62, v181
	ds_read_b128 v[0:3], v12
	ds_read_b128 v[4:7], v12 offset:1024
	ds_read_b128 v[8:11], v12 offset:2048
	ds_read_b128 v[12:15], v12 offset:3072
	ds_read_b128 v[16:19], v28
	ds_read_b128 v[20:23], v28 offset:1024
	ds_read_b128 v[24:27], v28 offset:2048
	ds_read_b128 v[28:31], v28 offset:3072
	s_add_u32 s40, s40, 0x200000
	s_addc_u32 s41, s41, 0
	s_mov_b32 m0, s45
	v_lshl_add_u64 v[220:221], s[40:41], 0, v[162:163]
	ds_read_b128 v[188:191], v185 offset:32768
	ds_read_b128 v[192:195], v185 offset:33792
	ds_read_b128 v[196:199], v185 offset:34816
	ds_read_b128 v[200:203], v185 offset:35840
	ds_read_b128 v[204:207], v185 offset:36864
	ds_read_b128 v[208:211], v185 offset:37888
	ds_read_b128 v[212:215], v185 offset:38912
	ds_read_b128 v[216:219], v185 offset:39936
	global_load_lds_dwordx4 v[220:221], off
	v_lshl_add_u64 v[220:221], s[40:41], 0, v[160:161]
	s_mov_b32 m0, s46
	s_nop 0
	global_load_lds_dwordx4 v[220:221], off
	s_waitcnt vmcnt(8)
	s_waitcnt lgkmcnt(0)
	s_barrier
	s_setprio 1
	s_waitcnt lgkmcnt(0)
	v_mfma_scale_f32_16x16x128_f8f6f4 v[156:159], v[0:7], v[188:195], v[156:159], v186, v186 op_sel_hi:[0,0,0]
	v_mfma_scale_f32_16x16x128_f8f6f4 v[152:155], v[8:15], v[188:195], v[152:155], v186, v186 op_sel_hi:[0,0,0]
	v_mfma_scale_f32_16x16x128_f8f6f4 v[148:151], v[0:7], v[196:203], v[148:151], v186, v186 op_sel_hi:[0,0,0]
	v_mfma_scale_f32_16x16x128_f8f6f4 v[144:147], v[8:15], v[196:203], v[144:147], v186, v186 op_sel_hi:[0,0,0]
	v_mfma_scale_f32_16x16x128_f8f6f4 v[140:143], v[0:7], v[204:211], v[140:143], v186, v186 op_sel_hi:[0,0,0]
	v_mfma_scale_f32_16x16x128_f8f6f4 v[124:127], v[8:15], v[204:211], v[124:127], v186, v186 op_sel_hi:[0,0,0]
	v_mfma_scale_f32_16x16x128_f8f6f4 v[116:119], v[0:7], v[212:219], v[116:119], v186, v186 op_sel_hi:[0,0,0]
	v_mfma_scale_f32_16x16x128_f8f6f4 v[108:111], v[8:15], v[212:219], v[108:111], v186, v186 op_sel_hi:[0,0,0]
	s_setprio 0
	s_setprio 1
	v_mfma_scale_f32_16x16x128_f8f6f4 v[136:139], v[16:23], v[188:195], v[136:139], v186, v186 op_sel_hi:[0,0,0]
	v_mfma_scale_f32_16x16x128_f8f6f4 v[132:135], v[24:31], v[188:195], v[132:135], v186, v186 op_sel_hi:[0,0,0]
	v_mfma_scale_f32_16x16x128_f8f6f4 v[128:131], v[16:23], v[196:203], v[128:131], v186, v186 op_sel_hi:[0,0,0]
	v_mfma_scale_f32_16x16x128_f8f6f4 v[120:123], v[24:31], v[196:203], v[120:123], v186, v186 op_sel_hi:[0,0,0]
	v_mfma_scale_f32_16x16x128_f8f6f4 v[112:115], v[16:23], v[204:211], v[112:115], v186, v186 op_sel_hi:[0,0,0]
	v_mfma_scale_f32_16x16x128_f8f6f4 v[104:107], v[24:31], v[204:211], v[104:107], v186, v186 op_sel_hi:[0,0,0]
	v_mfma_scale_f32_16x16x128_f8f6f4 v[100:103], v[16:23], v[212:219], v[100:103], v186, v186 op_sel_hi:[0,0,0]
	v_mfma_scale_f32_16x16x128_f8f6f4 v[96:99], v[24:31], v[212:219], v[96:99], v186, v186 op_sel_hi:[0,0,0]
	s_setprio 0
	s_barrier
	s_add_i32 s40, s61, s42
	v_lshl_add_u64 v[172:173], v[172:173], 0, s[6:7]
	s_mov_b32 m0, s40
	ds_read_b128 v[188:191], v185 offset:49152
	ds_read_b128 v[192:195], v185 offset:50176
	ds_read_b128 v[196:199], v185 offset:51200
	ds_read_b128 v[200:203], v185 offset:52224
	ds_read_b128 v[204:207], v185 offset:53248
	ds_read_b128 v[208:211], v185 offset:54272
	ds_read_b128 v[212:215], v185 offset:55296
	ds_read_b128 v[216:219], v185 offset:56320
	global_load_lds_dwordx4 v[172:173], off
	s_add_i32 m0, s40, 0x2000
	s_add_u32 s38, s38, 0x200080
	v_lshl_add_u64 v[172:173], v[174:175], 0, s[6:7]
	s_addc_u32 s39, s39, 0
	s_add_i32 s40, s62, s42
	global_load_lds_dwordx4 v[172:173], off
	v_lshl_add_u64 v[172:173], s[38:39], 0, v[162:163]
	s_mov_b32 m0, s40
	s_nop 0
	global_load_lds_dwordx4 v[172:173], off
	v_lshl_add_u64 v[172:173], s[38:39], 0, v[160:161]
	s_add_i32 m0, s40, 0x2000
	s_nop 0
	global_load_lds_dwordx4 v[172:173], off
	v_lshl_add_u64 v[172:173], v[176:177], 0, s[6:7]
	s_mov_b32 m0, s51
	s_nop 0
	global_load_lds_dwordx4 v[172:173], off
	v_lshl_add_u64 v[172:173], v[178:179], 0, s[6:7]
	s_mov_b32 m0, s52
	s_nop 0
	global_load_lds_dwordx4 v[172:173], off
	s_waitcnt vmcnt(8)
	s_waitcnt lgkmcnt(0)
	s_barrier
	s_setprio 1
	s_waitcnt lgkmcnt(0)
	v_mfma_scale_f32_16x16x128_f8f6f4 v[92:95], v[0:7], v[188:195], v[92:95], v186, v186 op_sel_hi:[0,0,0]
	v_mfma_scale_f32_16x16x128_f8f6f4 v[88:91], v[8:15], v[188:195], v[88:91], v186, v186 op_sel_hi:[0,0,0]
	v_mfma_scale_f32_16x16x128_f8f6f4 v[84:87], v[0:7], v[196:203], v[84:87], v186, v186 op_sel_hi:[0,0,0]
	v_mfma_scale_f32_16x16x128_f8f6f4 v[80:83], v[8:15], v[196:203], v[80:83], v186, v186 op_sel_hi:[0,0,0]
	v_mfma_scale_f32_16x16x128_f8f6f4 v[76:79], v[0:7], v[204:211], v[76:79], v186, v186 op_sel_hi:[0,0,0]
	v_mfma_scale_f32_16x16x128_f8f6f4 v[64:67], v[8:15], v[204:211], v[64:67], v186, v186 op_sel_hi:[0,0,0]
	v_mfma_scale_f32_16x16x128_f8f6f4 v[52:55], v[0:7], v[212:219], v[52:55], v186, v186 op_sel_hi:[0,0,0]
	v_mfma_scale_f32_16x16x128_f8f6f4 v[44:47], v[8:15], v[212:219], v[44:47], v186, v186 op_sel_hi:[0,0,0]
	s_setprio 0
	s_setprio 1
	v_mfma_scale_f32_16x16x128_f8f6f4 v[72:75], v[16:23], v[188:195], v[72:75], v186, v186 op_sel_hi:[0,0,0]
	v_mfma_scale_f32_16x16x128_f8f6f4 v[68:71], v[24:31], v[188:195], v[68:71], v186, v186 op_sel_hi:[0,0,0]
	v_mfma_scale_f32_16x16x128_f8f6f4 v[60:63], v[16:23], v[196:203], v[60:63], v186, v186 op_sel_hi:[0,0,0]
	v_mfma_scale_f32_16x16x128_f8f6f4 v[56:59], v[24:31], v[196:203], v[56:59], v186, v186 op_sel_hi:[0,0,0]
	v_mfma_scale_f32_16x16x128_f8f6f4 v[48:51], v[16:23], v[204:211], v[48:51], v186, v186 op_sel_hi:[0,0,0]
	v_mfma_scale_f32_16x16x128_f8f6f4 v[40:43], v[24:31], v[204:211], v[40:43], v186, v186 op_sel_hi:[0,0,0]
	v_mfma_scale_f32_16x16x128_f8f6f4 v[36:39], v[16:23], v[212:219], v[36:39], v186, v186 op_sel_hi:[0,0,0]
	v_mfma_scale_f32_16x16x128_f8f6f4 v[32:35], v[24:31], v[212:219], v[32:35], v186, v186 op_sel_hi:[0,0,0]
	s_setprio 0
	s_barrier
	s_add_i32 s60, s60, 2
	s_add_u32 s36, s36, 0x100
	s_addc_u32 s37, s37, 0
	s_add_u32 s58, s58, 0x100
	s_addc_u32 s59, s59, 0
	s_cmpk_lt_u32 s60, 0x7e
	s_cbranch_scc1 .LBB0_1019
	s_nop 15
	s_nop 15
	s_andn2_b64 vcc, exec, s[12:13]
	s_cbranch_vccnz .LBB0_1022
	s_barrier
